# attention FIXREF loop: K/V LDS-DMA sources as SGPR base + lane offset (no per-lane 64-bit VALU adds), 6-step unrolled copy with ring-slot offsets as immediates (no LDS-base v_add), m0 written directly
# speedup vs baseline: 1.0180x; 1.0180x over previous
; #define WAIT_BAR(N) asm volatile("s_waitcnt vmcnt(" #N ") lgkmcnt(0)\n\ts_barrier":::"memory")
;   #define DMA_K(t,slot) glds16(ksrc+(long)(t)*4096,(unsigned)__builtin_amdgcn_readfirstlane(kdst+(slot)))
;   #define DMA_V(t,slot) glds16(vsrc+(long)(t)*4096,(unsigned)__builtin_amdgcn_readfirstlane(vdst+(slot)))
;   #define CMASK(P0,P1,t) do{}while(0)
;   #define ROT() do{sl_prev=sl_cur;sl_cur=sl_next;sl_next=(sl_next==(NSLOT-1)*SLOTB)?0:sl_next+SLOTB;}while(0)
;   #define CMASK(P0,P1,t) do{}while(0)
;   #define CMASK(P0,P1,t) do{}while(0)
; template<int THRL,bool FIXREF> __device__ __forceinline__ void attn_unit(const float*gq,const float*tab,const int tq0,const bf16*Qw0,const bf16*__restrict__ Kl,const bf16*__restrict__ Vl,const int NT,bf16*Ow0,char*shm){
;     ...
;   float mhat=0.f,l_reg=0.f;f32x16 o[2];o[0]=f32x16{};o[1]=f32x16{};f32x16 negm=f32x16{};asm volatile("":"+v"(negm));
;     ...
;   bool resc=false;
;     ...
;   f32x16 pA0,pA1,pB0,pB1;
;   int sl_prev=0,sl_cur=0,sl_next=SLOTB;
;     ...
;   DMA_K(2,2*SLOTB);
;   WAIT_BAR(3);
;   qkt(pA0,pA1,Kbase,qr,negm,r32,hi);asm volatile("s_nop 15\n\ts_nop 7":"+v"(pA0),"+v"(pA1));CMASK(pA0,pA1,0);
;   START(pA0,pA1);
;   _Pragma("unroll") for(int r=0;r<16;++r)pA1[r]=__builtin_amdgcn_exp2f(pA1[r]);
;   WAIT_BAR(0);
;   DMA_K(3,0);DMA_V(1,SLOTB);
;   ROT();
;   kload8(kf,kp0+sl_cur);
;   WAIT_BAR(2);
.LBB0_276:
	v_lshlrev_b32_e32 v0, 10, v228
	v_lshlrev_b32_e32 v2, 4, v227
	v_add3_u32 v230, 0, v0, v2
	v_mov_b32_e32 v2, v1
	v_mov_b32_e32 v3, v1
	v_mov_b32_e32 v4, v1
	v_mov_b32_e32 v5, v1
	v_mov_b32_e32 v6, v1
	v_mov_b32_e32 v7, v1
	v_mov_b32_e32 v8, v1
	v_mov_b32_e32 v9, v1
	v_mov_b32_e32 v10, v1
	v_mov_b32_e32 v11, v1
	v_mov_b32_e32 v12, v1
	v_mov_b32_e32 v13, v1
	v_mov_b32_e32 v14, v1
	v_mov_b32_e32 v15, v1
	s_cmp_lg_u32 0, -1
	v_mov_b32_e32 v0, v1
	v_mov_b64_e32 v[16:17], v[14:15]
	s_cselect_b32 s4, 0, 0
	v_mov_b64_e32 v[14:15], v[12:13]
	v_mov_b64_e32 v[12:13], v[10:11]
	v_mov_b64_e32 v[10:11], v[8:9]
	v_mov_b64_e32 v[8:9], v[6:7]
	v_mov_b64_e32 v[6:7], v[4:5]
	v_mov_b64_e32 v[4:5], v[2:3]
	v_mov_b64_e32 v[2:3], v[0:1]
	s_add_i32 s5, s4, s7
	v_lshl_add_u64 v[18:19], v[194:195], 0, s[16:17]
	s_add_i32 s4, s5, 0x4000
	s_mov_b32 s6, m0
	s_mov_b32 m0, s4
	s_nop 0
	global_load_lds_dwordx4 v[18:19], off
	s_mov_b32 m0, s6
	s_waitcnt vmcnt(3) lgkmcnt(0)
	s_barrier
	ds_read_b128 v[18:21], v230
	ds_read_b128 v[86:89], v230 offset:512
	v_cvt_pk_bf16_f32 v158, v22, v23
	v_cvt_pk_bf16_f32 v159, v24, v25
	v_cvt_pk_bf16_f32 v160, v38, v39
	v_cvt_pk_bf16_f32 v161, v40, v41
	v_cvt_pk_bf16_f32 v150, v54, v55
	v_cvt_pk_bf16_f32 v151, v56, v57
	s_waitcnt lgkmcnt(1)
	v_mfma_f32_32x32x16_bf16 v[34:49], v[18:21], v[158:161], v[2:17]
	ds_read_b128 v[54:57], v230 offset:2560
	v_cvt_pk_bf16_f32 v152, v58, v59
	v_cvt_pk_bf16_f32 v153, v62, v63
	v_cvt_pk_bf16_f32 v142, v82, v69
	v_cvt_pk_bf16_f32 v145, v76, v71
	ds_read_b128 v[68:71], v230 offset:4608
	v_cvt_pk_bf16_f32 v143, v80, v73
	s_waitcnt lgkmcnt(2)
	v_mfma_f32_32x32x16_bf16 v[18:33], v[86:89], v[158:161], v[2:17]
	ds_read_b128 v[86:89], v230 offset:2048
	v_cvt_pk_bf16_f32 v144, v78, v75
	v_cvt_pk_bf16_f32 v134, v52, v53
	v_cvt_pk_bf16_f32 v135, v60, v61
	v_cvt_pk_bf16_f32 v136, v66, v67
	v_cvt_pk_bf16_f32 v137, v64, v65
	s_mov_b64 s[14:15], 0x6000
	s_waitcnt lgkmcnt(2)
	v_mfma_f32_32x32x16_bf16 v[18:33], v[54:57], v[150:153], v[18:33]
	ds_read_b128 v[54:57], v230 offset:4096
	s_add_i32 s5, s5, 0x8000
	v_lshlrev_b32_e32 v0, 1, v84
	v_and_b32_e32 v231, 32, v0
	v_lshlrev_b32_e32 v0, 3, v84
	v_lshlrev_b32_e32 v52, 4, v84
	v_and_b32_e32 v52, 0xc0, v52
	s_waitcnt lgkmcnt(1)
	v_mfma_f32_32x32x16_bf16 v[34:49], v[86:89], v[150:153], v[34:49]
	v_and_b32_e32 v232, 24, v0
	v_lshl_or_b32 v229, v228, 8, v52
	v_add_u32_e32 v52, 0, v231
	s_mov_b32 s10, 1
	v_add3_u32 v233, v52, v232, v229
	s_mov_b32 s4, 0
	s_movk_i32 s31, 0x4000
	s_waitcnt lgkmcnt(0)
	v_mfma_f32_32x32x16_bf16 v[34:49], v[54:57], v[142:145], v[34:49]
	ds_read_b128 v[54:57], v230 offset:6656
	ds_read_b128 v[72:75], v230 offset:6144
	s_cmp_lt_u32 s55, 7
	v_mfma_f32_32x32x16_bf16 v[18:33], v[68:71], v[142:145], v[18:33]
	s_waitcnt lgkmcnt(0)
	v_mfma_f32_32x32x16_bf16 v[34:49], v[72:75], v[134:137], v[34:49]
	v_mfma_f32_32x32x16_bf16 v[18:33], v[54:57], v[134:137], v[18:33]
	s_nop 15
	s_nop 7
	s_waitcnt vmcnt(0) lgkmcnt(0)
	s_barrier
	s_nop 10
	v_exp_f32_e32 v82, v34
	v_exp_f32_e32 v83, v35
	v_exp_f32_e32 v66, v18
	v_exp_f32_e32 v67, v19
	v_lshl_add_u64 v[18:19], v[194:195], 0, s[14:15]
	s_mov_b32 s6, m0
	s_mov_b32 m0, s18
	s_nop 0
	global_load_lds_dwordx4 v[18:19], off
	s_mov_b32 m0, s6
	s_mov_b64 s[6:7], 0x2000
	v_lshl_add_u64 v[196:197], v[50:51], 0, s[6:7]
	s_mov_b32 s6, m0
	s_mov_b32 m0, s5
	s_nop 0
	global_load_lds_dwordx4 v[196:197], off
	s_mov_b32 m0, s6
	ds_read_b128 v[190:193], v230 offset:8192
	ds_read_b128 v[186:189], v230 offset:8704
	ds_read_b128 v[182:185], v230 offset:10240
	ds_read_b128 v[178:181], v230 offset:10752
	ds_read_b128 v[174:177], v230 offset:12288
	ds_read_b128 v[170:173], v230 offset:12800
	ds_read_b128 v[166:169], v230 offset:14336
	ds_read_b128 v[162:165], v230 offset:14848
	v_exp_f32_e32 v84, v36
	v_exp_f32_e32 v85, v37
	v_exp_f32_e32 v86, v38
	v_exp_f32_e32 v87, v39
	v_exp_f32_e32 v88, v40
	v_exp_f32_e32 v89, v41
	v_exp_f32_e32 v90, v42
	v_exp_f32_e32 v91, v43
	v_exp_f32_e32 v92, v44
	v_exp_f32_e32 v93, v45
	v_exp_f32_e32 v94, v46
	v_exp_f32_e32 v95, v47
	v_exp_f32_e32 v96, v48
	v_exp_f32_e32 v97, v49
	v_exp_f32_e32 v68, v20
	v_exp_f32_e32 v69, v21
	v_exp_f32_e32 v70, v22
	v_exp_f32_e32 v71, v23
	v_exp_f32_e32 v72, v24
	v_exp_f32_e32 v73, v25
	v_exp_f32_e32 v74, v26
	v_exp_f32_e32 v75, v27
	v_exp_f32_e32 v76, v28
	v_exp_f32_e32 v77, v29
	v_exp_f32_e32 v78, v30
	v_exp_f32_e32 v79, v31
	v_exp_f32_e32 v80, v32
	v_exp_f32_e32 v81, v33
	s_waitcnt vmcnt(2) lgkmcnt(0)
	s_barrier
	s_cbranch_scc1 .LBB0_287
	v_lshl_add_u64 v[56:57], v[50:51], 0, s[14:15]
	s_mov_b64 s[4:5], 0xa000
	v_mov_b32_e32 v50, 0
	v_lshl_add_u64 v[58:59], v[194:195], 0, s[4:5]
	s_movk_i32 s30, 0x2000
	s_mov_b32 s7, 0
	s_mov_b32 s10, 6
	v_lshlrev_b32_e32 v240, 4, v224
	v_sub_u32_e32 v241, v56, v58
	v_readfirstlane_b32 s100, v58
	v_readfirstlane_b32 s101, v59
	v_add_u32_e32 v241, v241, v240
	s_nop 3
	s_sub_u32 s100, s100, 0x2000
	s_subb_u32 s101, s101, 0
	v_mov_b32_e32 v18, 0
	v_mov_b32_e32 v19, v50
	v_mov_b32_e32 v20, v50
	v_mov_b32_e32 v21, v50
	v_mov_b32_e32 v22, v50
	v_mov_b32_e32 v23, v50
	v_mov_b32_e32 v24, v50
	v_mov_b32_e32 v25, v50
	v_mov_b32_e32 v26, v50
	v_mov_b32_e32 v27, v50
	v_mov_b32_e32 v28, v50
	v_mov_b32_e32 v29, v50
	v_mov_b32_e32 v30, v50
	v_mov_b32_e32 v31, v50
	v_mov_b32_e32 v32, v50
	v_mov_b32_e32 v33, v50
	v_mov_b32_e32 v34, 0
	v_mov_b32_e32 v35, v50
	v_mov_b32_e32 v36, v50
	v_mov_b32_e32 v37, v50
	v_mov_b32_e32 v38, v50
	v_mov_b32_e32 v39, v50
	v_mov_b32_e32 v40, v50
	v_mov_b32_e32 v41, v50
	v_mov_b32_e32 v42, v50
	v_mov_b32_e32 v43, v50
	v_mov_b32_e32 v44, v50
	v_mov_b32_e32 v45, v50
	v_mov_b32_e32 v46, v50
	v_mov_b32_e32 v47, v50
	v_mov_b32_e32 v48, v50
	v_mov_b32_e32 v49, v50
	s_add_i32 s5, s10, 4
	s_cmp_lt_u32 s5, s55
	s_cbranch_scc0 .LBB0_278
; #define WAIT_BAR(N) asm volatile("s_waitcnt vmcnt(" #N ") lgkmcnt(0)\n\ts_barrier":::"memory")
;   #define RESC() do{ if(resc){ asm volatile("s_waitcnt lgkmcnt(0)":::"memory"); \
;       _Pragma("unroll") for(int d_=0;d_<2;++d_) _Pragma("unroll") for(int r=0;r<16;++r)o[d_][r]*=wsf[crow(r,hi)]; } }while(0)
;   #define ROT() do{sl_prev=sl_cur;sl_cur=sl_next;sl_next=(sl_next==(NSLOT-1)*SLOTB)?0:sl_next+SLOTB;}while(0)
; template<int THRL,bool FIXREF> __device__ __forceinline__ void attn_unit(const float*gq,const float*tab,const int tq0,const bf16*Qw0,const bf16*__restrict__ Kl,const bf16*__restrict__ Vl,const int NT,bf16*Ow0,char*shm){
;     ...
;   int t=1;
;     ...
;   for(;t+5<NT;t+=2){
;     STEP(pB0,pB1,pA0,pA1,t,true,true,true);     WAIT_BAR(2); RESC(); ROT();
;     STEP(pA0,pA1,pB0,pB1,t+1,true,true,true);   WAIT_BAR(2); RESC(); ROT();
.Lattn6:
	ds_read_b64_tr_b16 v[52:53], v233 offset:24576
	ds_read_b64_tr_b16 v[54:55], v233 offset:25088
	v_add_f32_e32 v60, v82, v83
	v_add_f32_e32 v60, v84, v60
	v_add_f32_e32 v60, v85, v60
	v_add_f32_e32 v60, v86, v60
	v_add_f32_e32 v64, v87, v60
	v_cvt_pk_bf16_f32 v154, v82, v83
	v_cvt_pk_bf16_f32 v155, v84, v85
	s_waitcnt lgkmcnt(9)
	v_mfma_f32_32x32x16_bf16 v[114:129], v[190:193], v[158:161], v[2:17]
	ds_read_b64_tr_b16 v[60:61], v233 offset:28672
	ds_read_b64_tr_b16 v[62:63], v233 offset:29184
	v_add_f32_e32 v64, v88, v64
	v_add_f32_e32 v64, v89, v64
	v_add_f32_e32 v64, v90, v64
	v_add_f32_e32 v64, v91, v64
	v_cvt_pk_bf16_f32 v156, v86, v87
	v_cvt_pk_bf16_f32 v157, v88, v89
	s_waitcnt lgkmcnt(10)
	v_mfma_f32_32x32x16_bf16 v[98:113], v[186:189], v[158:161], v[2:17]
	ds_read_b64_tr_b16 v[82:83], v233 offset:25600
	ds_read_b64_tr_b16 v[84:85], v233 offset:26112
	v_add_f32_e32 v64, v92, v64
	v_add_f32_e32 v64, v93, v64
	v_add_f32_e32 v64, v94, v64
	v_add_f32_e32 v64, v95, v64
	v_cvt_pk_bf16_f32 v146, v90, v91
	v_cvt_pk_bf16_f32 v147, v92, v93
	s_waitcnt lgkmcnt(11)
	v_mfma_f32_32x32x16_bf16 v[114:129], v[182:185], v[150:153], v[114:129]
	ds_read_b64_tr_b16 v[86:87], v233 offset:29696
	ds_read_b64_tr_b16 v[88:89], v233 offset:30208
	v_add_f32_e32 v64, v96, v64
	v_add_f32_e32 v64, v97, v64
	v_add_f32_e32 v64, v66, v64
	v_add_f32_e32 v64, v67, v64
	v_cvt_pk_bf16_f32 v148, v94, v95
	v_cvt_pk_bf16_f32 v149, v96, v97
	s_waitcnt lgkmcnt(12)
	v_mfma_f32_32x32x16_bf16 v[98:113], v[178:181], v[150:153], v[98:113]
	ds_read_b64_tr_b16 v[90:91], v233 offset:26624
	ds_read_b64_tr_b16 v[92:93], v233 offset:27136
	v_add_f32_e32 v64, v68, v64
	v_add_f32_e32 v64, v69, v64
	v_add_f32_e32 v64, v70, v64
	v_add_f32_e32 v94, v71, v64
	v_cvt_pk_bf16_f32 v138, v66, v67
	v_cvt_pk_bf16_f32 v139, v68, v69
	s_waitcnt lgkmcnt(13)
	v_mfma_f32_32x32x16_bf16 v[114:129], v[174:177], v[142:145], v[114:129]
	ds_read_b64_tr_b16 v[64:65], v233 offset:30720
	ds_read_b64_tr_b16 v[66:67], v233 offset:31232
	v_add_f32_e32 v68, v72, v94
	v_add_f32_e32 v68, v73, v68
	v_add_f32_e32 v68, v74, v68
	v_add_f32_e32 v94, v75, v68
	v_cvt_pk_bf16_f32 v140, v70, v71
	v_cvt_pk_bf16_f32 v141, v72, v73
	s_waitcnt lgkmcnt(14)
	v_mfma_f32_32x32x16_bf16 v[98:113], v[170:173], v[142:145], v[98:113]
	ds_read_b64_tr_b16 v[68:69], v233 offset:27648
	ds_read_b64_tr_b16 v[70:71], v233 offset:28160
	v_add_f32_e32 v72, v76, v94
	v_add_f32_e32 v72, v77, v72
	v_add_f32_e32 v72, v78, v72
	v_add_f32_e32 v94, v79, v72
	v_cvt_pk_bf16_f32 v130, v74, v75
	v_cvt_pk_bf16_f32 v131, v76, v77
	s_waitcnt lgkmcnt(14)
	v_mfma_f32_32x32x16_bf16 v[114:129], v[166:169], v[134:137], v[114:129]
	ds_read_b64_tr_b16 v[72:73], v233 offset:31744
	ds_read_b64_tr_b16 v[74:75], v233 offset:32256
	v_add_f32_e32 v51, v80, v94
	v_add_f32_e32 v51, v81, v51
	v_cvt_pk_bf16_f32 v132, v78, v79
	v_cvt_pk_bf16_f32 v133, v80, v81
	v_mfma_f32_32x32x16_bf16 v[98:113], v[162:165], v[134:137], v[98:113]
	s_add_i32 m0, s18, 0x2000
	s_nop 0
	global_load_lds_dwordx4 v240, s[100:101]
	s_add_i32 m0, s19, 0x4000
	s_nop 0
	global_load_lds_dwordx4 v241, s[100:101]
	s_waitcnt lgkmcnt(14)
	v_mfma_f32_32x32x16_bf16 v[18:33], v[154:157], v[52:55], v[18:33]
	s_add_u32 s100, s100, 0x2000
	s_addc_u32 s101, s101, 0
	v_exp_f32_e32 v114, v114
	v_exp_f32_e32 v115, v115
	v_exp_f32_e32 v116, v116
	v_exp_f32_e32 v117, v117
	s_waitcnt lgkmcnt(12)
	v_mfma_f32_32x32x16_bf16 v[34:49], v[154:157], v[60:63], v[34:49]
	v_exp_f32_e32 v118, v118
	v_exp_f32_e32 v119, v119
	v_exp_f32_e32 v120, v120
	v_exp_f32_e32 v121, v121
	ds_read_b128 v[60:63], v230 offset:16384
	ds_read_b128 v[162:165], v230 offset:16896
	s_waitcnt lgkmcnt(12)
	v_mfma_f32_32x32x16_bf16 v[18:33], v[146:149], v[82:85], v[18:33]
	v_exp_f32_e32 v122, v122
	v_exp_f32_e32 v123, v123
	v_exp_f32_e32 v124, v124
	v_exp_f32_e32 v125, v125
	ds_read_b128 v[166:169], v230 offset:18432
	ds_read_b128 v[170:173], v230 offset:18944
	s_waitcnt lgkmcnt(12)
	v_mfma_f32_32x32x16_bf16 v[34:49], v[146:149], v[86:89], v[34:49]
	v_exp_f32_e32 v126, v126
	v_exp_f32_e32 v127, v127
	v_exp_f32_e32 v128, v128
	v_exp_f32_e32 v129, v129
	ds_read_b128 v[174:177], v230 offset:20480
	ds_read_b128 v[178:181], v230 offset:20992
	s_waitcnt lgkmcnt(12)
	v_mfma_f32_32x32x16_bf16 v[18:33], v[138:141], v[90:93], v[18:33]
	v_exp_f32_e32 v98, v98
	v_exp_f32_e32 v99, v99
	v_exp_f32_e32 v100, v100
	v_exp_f32_e32 v101, v101
	ds_read_b128 v[182:185], v230 offset:22528
	ds_read_b128 v[52:55], v230 offset:23040
	s_waitcnt lgkmcnt(12)
	v_mfma_f32_32x32x16_bf16 v[34:49], v[138:141], v[64:67], v[34:49]
	v_exp_f32_e32 v102, v102
	v_exp_f32_e32 v103, v103
	v_exp_f32_e32 v104, v104
	v_exp_f32_e32 v105, v105
	s_waitcnt lgkmcnt(10)
	v_mfma_f32_32x32x16_bf16 v[18:33], v[130:133], v[68:71], v[18:33]
	v_exp_f32_e32 v106, v106
	v_exp_f32_e32 v107, v107
	v_exp_f32_e32 v108, v108
	v_exp_f32_e32 v109, v109
	s_waitcnt lgkmcnt(8)
	v_mfma_f32_32x32x16_bf16 v[34:49], v[130:133], v[72:75], v[34:49]
	v_exp_f32_e32 v110, v110
	v_exp_f32_e32 v111, v111
	v_exp_f32_e32 v112, v112
	v_exp_f32_e32 v113, v113
	s_waitcnt vmcnt(2) lgkmcnt(0)
	s_barrier
; #define WAIT_BAR(N) asm volatile("s_waitcnt vmcnt(" #N ") lgkmcnt(0)\n\ts_barrier":::"memory")
;   #define RESC() do{ if(resc){ asm volatile("s_waitcnt lgkmcnt(0)":::"memory"); \
;       _Pragma("unroll") for(int d_=0;d_<2;++d_) _Pragma("unroll") for(int r=0;r<16;++r)o[d_][r]*=wsf[crow(r,hi)]; } }while(0)
;   #define ROT() do{sl_prev=sl_cur;sl_cur=sl_next;sl_next=(sl_next==(NSLOT-1)*SLOTB)?0:sl_next+SLOTB;}while(0)
; template<int THRL,bool FIXREF> __device__ __forceinline__ void attn_unit(const float*gq,const float*tab,const int tq0,const bf16*Qw0,const bf16*__restrict__ Kl,const bf16*__restrict__ Vl,const int NT,bf16*Ow0,char*shm){
;     ...
;   int t=1;
;     ...
;   for(;t+5<NT;t+=2){
;     STEP(pB0,pB1,pA0,pA1,t,true,true,true);     WAIT_BAR(2); RESC(); ROT();
;     STEP(pA0,pA1,pB0,pB1,t+1,true,true,true);   WAIT_BAR(2); RESC(); ROT();
	ds_read_b64_tr_b16 v[186:187], v233 offset:32768
	ds_read_b64_tr_b16 v[188:189], v233 offset:33280
	s_waitcnt lgkmcnt(9)
	v_mfma_f32_32x32x16_bf16 v[82:97], v[60:63], v[158:161], v[2:17]
	v_add_f32_e32 v65, v114, v115
	v_add_f32_e32 v65, v116, v65
	v_add_f32_e32 v65, v117, v65
	v_add_f32_e32 v65, v118, v65
	v_add_f32_e32 v65, v119, v65
	v_cvt_pk_bf16_f32 v154, v114, v115
	v_cvt_pk_bf16_f32 v155, v116, v117
	ds_read_b64_tr_b16 v[60:61], v233 offset:36864
	ds_read_b64_tr_b16 v[62:63], v233 offset:37376
	s_waitcnt lgkmcnt(10)
	v_mfma_f32_32x32x16_bf16 v[66:81], v[162:165], v[158:161], v[2:17]
	v_add_f32_e32 v65, v120, v65
	v_add_f32_e32 v65, v121, v65
	v_add_f32_e32 v65, v122, v65
	v_add_f32_e32 v65, v123, v65
	v_cvt_pk_bf16_f32 v156, v118, v119
	v_cvt_pk_bf16_f32 v157, v120, v121
	ds_read_b64_tr_b16 v[114:115], v233 offset:33792
	ds_read_b64_tr_b16 v[116:117], v233 offset:34304
	s_waitcnt lgkmcnt(11)
	v_mfma_f32_32x32x16_bf16 v[82:97], v[166:169], v[150:153], v[82:97]
	v_add_f32_e32 v65, v124, v65
	v_add_f32_e32 v65, v125, v65
	v_add_f32_e32 v65, v126, v65
	v_add_f32_e32 v65, v127, v65
	v_cvt_pk_bf16_f32 v146, v122, v123
	v_cvt_pk_bf16_f32 v147, v124, v125
	ds_read_b64_tr_b16 v[118:119], v233 offset:37888
	ds_read_b64_tr_b16 v[120:121], v233 offset:38400
	s_waitcnt lgkmcnt(12)
	v_mfma_f32_32x32x16_bf16 v[66:81], v[170:173], v[150:153], v[66:81]
	v_add_f32_e32 v65, v128, v65
	v_add_f32_e32 v65, v129, v65
	v_add_f32_e32 v65, v98, v65
	v_add_f32_e32 v65, v99, v65
	v_cvt_pk_bf16_f32 v148, v126, v127
	v_cvt_pk_bf16_f32 v149, v128, v129
	ds_read_b64_tr_b16 v[122:123], v233 offset:34816
	ds_read_b64_tr_b16 v[124:125], v233 offset:35328
	s_waitcnt lgkmcnt(13)
	v_mfma_f32_32x32x16_bf16 v[82:97], v[174:177], v[142:145], v[82:97]
	v_add_f32_e32 v65, v100, v65
	v_add_f32_e32 v65, v101, v65
	v_add_f32_e32 v65, v102, v65
	v_add_f32_e32 v65, v103, v65
	v_cvt_pk_bf16_f32 v138, v98, v99
	v_cvt_pk_bf16_f32 v139, v100, v101
	ds_read_b64_tr_b16 v[98:99], v233 offset:38912
	ds_read_b64_tr_b16 v[100:101], v233 offset:39424
	s_waitcnt lgkmcnt(14)
	v_mfma_f32_32x32x16_bf16 v[66:81], v[178:181], v[142:145], v[66:81]
	v_add_f32_e32 v65, v104, v65
	v_add_f32_e32 v65, v105, v65
	v_add_f32_e32 v65, v106, v65
	v_add_f32_e32 v65, v107, v65
	v_cvt_pk_bf16_f32 v140, v102, v103
	v_cvt_pk_bf16_f32 v141, v104, v105
	ds_read_b64_tr_b16 v[102:103], v233 offset:35840
	ds_read_b64_tr_b16 v[104:105], v233 offset:36352
	s_waitcnt lgkmcnt(14)
	v_mfma_f32_32x32x16_bf16 v[82:97], v[182:185], v[134:137], v[82:97]
	v_add_f32_e32 v65, v108, v65
	v_add_f32_e32 v65, v109, v65
	v_add_f32_e32 v65, v110, v65
	v_add_f32_e32 v65, v111, v65
	v_cvt_pk_bf16_f32 v130, v106, v107
	v_cvt_pk_bf16_f32 v131, v108, v109
	ds_read_b64_tr_b16 v[106:107], v233 offset:39936
	ds_read_b64_tr_b16 v[108:109], v233 offset:40448
	v_mfma_f32_32x32x16_bf16 v[66:81], v[52:55], v[134:137], v[66:81]
	v_add_f32_e32 v52, v112, v65
	v_add_f32_e32 v52, v113, v52
	v_cvt_pk_bf16_f32 v132, v110, v111
	v_cvt_pk_bf16_f32 v133, v112, v113
	s_add_i32 m0, s18, 0x4000
	s_nop 0
	global_load_lds_dwordx4 v240, s[100:101]
	s_mov_b32 m0, s19
	s_nop 0
	global_load_lds_dwordx4 v241, s[100:101]
	s_waitcnt lgkmcnt(14)
	v_mfma_f32_32x32x16_bf16 v[18:33], v[154:157], v[186:189], v[18:33]
	s_add_u32 s100, s100, 0x2000
	s_addc_u32 s101, s101, 0
	v_exp_f32_e32 v82, v82
	v_exp_f32_e32 v83, v83
	v_exp_f32_e32 v84, v84
	v_exp_f32_e32 v85, v85
	s_waitcnt lgkmcnt(12)
	v_mfma_f32_32x32x16_bf16 v[34:49], v[154:157], v[60:63], v[34:49]
	v_exp_f32_e32 v86, v86
	v_exp_f32_e32 v87, v87
	v_exp_f32_e32 v88, v88
	v_exp_f32_e32 v89, v89
	ds_read_b128 v[190:193], v230
	ds_read_b128 v[186:189], v230 offset:512
	s_waitcnt lgkmcnt(12)
	v_mfma_f32_32x32x16_bf16 v[18:33], v[146:149], v[114:117], v[18:33]
	v_exp_f32_e32 v90, v90
	v_exp_f32_e32 v91, v91
	v_exp_f32_e32 v92, v92
	v_exp_f32_e32 v93, v93
	ds_read_b128 v[182:185], v230 offset:2048
	ds_read_b128 v[178:181], v230 offset:2560
	s_waitcnt lgkmcnt(12)
	v_mfma_f32_32x32x16_bf16 v[34:49], v[146:149], v[118:121], v[34:49]
	v_exp_f32_e32 v94, v94
	v_exp_f32_e32 v95, v95
	v_exp_f32_e32 v96, v96
	v_exp_f32_e32 v97, v97
	ds_read_b128 v[174:177], v230 offset:4096
	ds_read_b128 v[170:173], v230 offset:4608
	s_waitcnt lgkmcnt(12)
	v_mfma_f32_32x32x16_bf16 v[18:33], v[138:141], v[122:125], v[18:33]
	v_exp_f32_e32 v66, v66
	v_exp_f32_e32 v67, v67
	v_exp_f32_e32 v68, v68
	v_exp_f32_e32 v69, v69
	ds_read_b128 v[166:169], v230 offset:6144
	ds_read_b128 v[162:165], v230 offset:6656
	s_waitcnt lgkmcnt(12)
	v_mfma_f32_32x32x16_bf16 v[34:49], v[138:141], v[98:101], v[34:49]
	v_exp_f32_e32 v70, v70
	v_exp_f32_e32 v71, v71
	v_exp_f32_e32 v72, v72
	v_exp_f32_e32 v73, v73
	s_waitcnt lgkmcnt(10)
	v_mfma_f32_32x32x16_bf16 v[18:33], v[130:133], v[102:105], v[18:33]
	v_exp_f32_e32 v74, v74
	v_exp_f32_e32 v75, v75
	v_exp_f32_e32 v76, v76
	v_exp_f32_e32 v77, v77
	s_waitcnt lgkmcnt(8)
	v_mfma_f32_32x32x16_bf16 v[34:49], v[130:133], v[106:109], v[34:49]
	v_exp_f32_e32 v78, v78
	v_exp_f32_e32 v79, v79
	v_exp_f32_e32 v80, v80
	v_exp_f32_e32 v81, v81
	s_waitcnt vmcnt(2) lgkmcnt(0)
	s_barrier
; #define WAIT_BAR(N) asm volatile("s_waitcnt vmcnt(" #N ") lgkmcnt(0)\n\ts_barrier":::"memory")
;   #define RESC() do{ if(resc){ asm volatile("s_waitcnt lgkmcnt(0)":::"memory"); \
;       _Pragma("unroll") for(int d_=0;d_<2;++d_) _Pragma("unroll") for(int r=0;r<16;++r)o[d_][r]*=wsf[crow(r,hi)]; } }while(0)
;   #define ROT() do{sl_prev=sl_cur;sl_cur=sl_next;sl_next=(sl_next==(NSLOT-1)*SLOTB)?0:sl_next+SLOTB;}while(0)
; template<int THRL,bool FIXREF> __device__ __forceinline__ void attn_unit(const float*gq,const float*tab,const int tq0,const bf16*Qw0,const bf16*__restrict__ Kl,const bf16*__restrict__ Vl,const int NT,bf16*Ow0,char*shm){
;     ...
;   int t=1;
;     ...
;   for(;t+5<NT;t+=2){
;     STEP(pB0,pB1,pA0,pA1,t,true,true,true);     WAIT_BAR(2); RESC(); ROT();
;     STEP(pA0,pA1,pB0,pB1,t+1,true,true,true);   WAIT_BAR(2); RESC(); ROT();
	v_add_f32_e32 v50, v50, v51
	v_add_f32_e32 v50, v50, v52
	ds_read_b64_tr_b16 v[52:53], v233 offset:40960
	ds_read_b64_tr_b16 v[54:55], v233 offset:41472
	v_add_f32_e32 v60, v82, v83
	v_add_f32_e32 v60, v84, v60
	v_add_f32_e32 v60, v85, v60
	v_add_f32_e32 v60, v86, v60
	v_add_f32_e32 v64, v87, v60
	v_cvt_pk_bf16_f32 v154, v82, v83
	v_cvt_pk_bf16_f32 v155, v84, v85
	s_waitcnt lgkmcnt(9)
	v_mfma_f32_32x32x16_bf16 v[114:129], v[190:193], v[158:161], v[2:17]
	ds_read_b64_tr_b16 v[60:61], v233 offset:45056
	ds_read_b64_tr_b16 v[62:63], v233 offset:45568
	v_add_f32_e32 v64, v88, v64
	v_add_f32_e32 v64, v89, v64
	v_add_f32_e32 v64, v90, v64
	v_add_f32_e32 v64, v91, v64
	v_cvt_pk_bf16_f32 v156, v86, v87
	v_cvt_pk_bf16_f32 v157, v88, v89
	s_waitcnt lgkmcnt(10)
	v_mfma_f32_32x32x16_bf16 v[98:113], v[186:189], v[158:161], v[2:17]
	ds_read_b64_tr_b16 v[82:83], v233 offset:41984
	ds_read_b64_tr_b16 v[84:85], v233 offset:42496
	v_add_f32_e32 v64, v92, v64
	v_add_f32_e32 v64, v93, v64
	v_add_f32_e32 v64, v94, v64
	v_add_f32_e32 v64, v95, v64
	v_cvt_pk_bf16_f32 v146, v90, v91
	v_cvt_pk_bf16_f32 v147, v92, v93
	s_waitcnt lgkmcnt(11)
	v_mfma_f32_32x32x16_bf16 v[114:129], v[182:185], v[150:153], v[114:129]
	ds_read_b64_tr_b16 v[86:87], v233 offset:46080
	ds_read_b64_tr_b16 v[88:89], v233 offset:46592
	v_add_f32_e32 v64, v96, v64
	v_add_f32_e32 v64, v97, v64
	v_add_f32_e32 v64, v66, v64
	v_add_f32_e32 v64, v67, v64
	v_cvt_pk_bf16_f32 v148, v94, v95
	v_cvt_pk_bf16_f32 v149, v96, v97
	s_waitcnt lgkmcnt(12)
	v_mfma_f32_32x32x16_bf16 v[98:113], v[178:181], v[150:153], v[98:113]
	ds_read_b64_tr_b16 v[90:91], v233 offset:43008
	ds_read_b64_tr_b16 v[92:93], v233 offset:43520
	v_add_f32_e32 v64, v68, v64
	v_add_f32_e32 v64, v69, v64
	v_add_f32_e32 v64, v70, v64
	v_add_f32_e32 v94, v71, v64
	v_cvt_pk_bf16_f32 v138, v66, v67
	v_cvt_pk_bf16_f32 v139, v68, v69
	s_waitcnt lgkmcnt(13)
	v_mfma_f32_32x32x16_bf16 v[114:129], v[174:177], v[142:145], v[114:129]
	ds_read_b64_tr_b16 v[64:65], v233 offset:47104
	ds_read_b64_tr_b16 v[66:67], v233 offset:47616
	v_add_f32_e32 v68, v72, v94
	v_add_f32_e32 v68, v73, v68
	v_add_f32_e32 v68, v74, v68
	v_add_f32_e32 v94, v75, v68
	v_cvt_pk_bf16_f32 v140, v70, v71
	v_cvt_pk_bf16_f32 v141, v72, v73
	s_waitcnt lgkmcnt(14)
	v_mfma_f32_32x32x16_bf16 v[98:113], v[170:173], v[142:145], v[98:113]
	ds_read_b64_tr_b16 v[68:69], v233 offset:44032
	ds_read_b64_tr_b16 v[70:71], v233 offset:44544
	v_add_f32_e32 v72, v76, v94
	v_add_f32_e32 v72, v77, v72
	v_add_f32_e32 v72, v78, v72
	v_add_f32_e32 v94, v79, v72
	v_cvt_pk_bf16_f32 v130, v74, v75
	v_cvt_pk_bf16_f32 v131, v76, v77
	s_waitcnt lgkmcnt(14)
	v_mfma_f32_32x32x16_bf16 v[114:129], v[166:169], v[134:137], v[114:129]
	ds_read_b64_tr_b16 v[72:73], v233 offset:48128
	ds_read_b64_tr_b16 v[74:75], v233 offset:48640
	v_add_f32_e32 v51, v80, v94
	v_add_f32_e32 v51, v81, v51
	v_cvt_pk_bf16_f32 v132, v78, v79
	v_cvt_pk_bf16_f32 v133, v80, v81
	v_mfma_f32_32x32x16_bf16 v[98:113], v[162:165], v[134:137], v[98:113]
	s_mov_b32 m0, s18
	s_nop 0
	global_load_lds_dwordx4 v240, s[100:101]
	s_add_i32 m0, s19, 0x2000
	s_nop 0
	global_load_lds_dwordx4 v241, s[100:101]
	s_waitcnt lgkmcnt(14)
	v_mfma_f32_32x32x16_bf16 v[18:33], v[154:157], v[52:55], v[18:33]
	s_add_u32 s100, s100, 0x2000
	s_addc_u32 s101, s101, 0
	v_exp_f32_e32 v114, v114
	v_exp_f32_e32 v115, v115
	v_exp_f32_e32 v116, v116
	v_exp_f32_e32 v117, v117
	s_waitcnt lgkmcnt(12)
	v_mfma_f32_32x32x16_bf16 v[34:49], v[154:157], v[60:63], v[34:49]
	v_exp_f32_e32 v118, v118
	v_exp_f32_e32 v119, v119
	v_exp_f32_e32 v120, v120
	v_exp_f32_e32 v121, v121
	ds_read_b128 v[60:63], v230 offset:8192
	ds_read_b128 v[162:165], v230 offset:8704
	s_waitcnt lgkmcnt(12)
	v_mfma_f32_32x32x16_bf16 v[18:33], v[146:149], v[82:85], v[18:33]
	v_exp_f32_e32 v122, v122
	v_exp_f32_e32 v123, v123
	v_exp_f32_e32 v124, v124
	v_exp_f32_e32 v125, v125
	ds_read_b128 v[166:169], v230 offset:10240
	ds_read_b128 v[170:173], v230 offset:10752
	s_waitcnt lgkmcnt(12)
	v_mfma_f32_32x32x16_bf16 v[34:49], v[146:149], v[86:89], v[34:49]
	v_exp_f32_e32 v126, v126
	v_exp_f32_e32 v127, v127
	v_exp_f32_e32 v128, v128
	v_exp_f32_e32 v129, v129
	ds_read_b128 v[174:177], v230 offset:12288
	ds_read_b128 v[178:181], v230 offset:12800
	s_waitcnt lgkmcnt(12)
	v_mfma_f32_32x32x16_bf16 v[18:33], v[138:141], v[90:93], v[18:33]
	v_exp_f32_e32 v98, v98
	v_exp_f32_e32 v99, v99
	v_exp_f32_e32 v100, v100
	v_exp_f32_e32 v101, v101
	ds_read_b128 v[182:185], v230 offset:14336
	ds_read_b128 v[52:55], v230 offset:14848
	s_waitcnt lgkmcnt(12)
	v_mfma_f32_32x32x16_bf16 v[34:49], v[138:141], v[64:67], v[34:49]
	v_exp_f32_e32 v102, v102
	v_exp_f32_e32 v103, v103
	v_exp_f32_e32 v104, v104
	v_exp_f32_e32 v105, v105
	s_waitcnt lgkmcnt(10)
	v_mfma_f32_32x32x16_bf16 v[18:33], v[130:133], v[68:71], v[18:33]
	v_exp_f32_e32 v106, v106
	v_exp_f32_e32 v107, v107
	v_exp_f32_e32 v108, v108
	v_exp_f32_e32 v109, v109
	s_waitcnt lgkmcnt(8)
	v_mfma_f32_32x32x16_bf16 v[34:49], v[130:133], v[72:75], v[34:49]
	v_exp_f32_e32 v110, v110
	v_exp_f32_e32 v111, v111
	v_exp_f32_e32 v112, v112
	v_exp_f32_e32 v113, v113
	s_waitcnt vmcnt(2) lgkmcnt(0)
	s_barrier
; #define WAIT_BAR(N) asm volatile("s_waitcnt vmcnt(" #N ") lgkmcnt(0)\n\ts_barrier":::"memory")
;   #define RESC() do{ if(resc){ asm volatile("s_waitcnt lgkmcnt(0)":::"memory"); \
;       _Pragma("unroll") for(int d_=0;d_<2;++d_) _Pragma("unroll") for(int r=0;r<16;++r)o[d_][r]*=wsf[crow(r,hi)]; } }while(0)
;   #define ROT() do{sl_prev=sl_cur;sl_cur=sl_next;sl_next=(sl_next==(NSLOT-1)*SLOTB)?0:sl_next+SLOTB;}while(0)
; template<int THRL,bool FIXREF> __device__ __forceinline__ void attn_unit(const float*gq,const float*tab,const int tq0,const bf16*Qw0,const bf16*__restrict__ Kl,const bf16*__restrict__ Vl,const int NT,bf16*Ow0,char*shm){
;     ...
;   int t=1;
;     ...
;   for(;t+5<NT;t+=2){
;     STEP(pB0,pB1,pA0,pA1,t,true,true,true);     WAIT_BAR(2); RESC(); ROT();
;     STEP(pA0,pA1,pB0,pB1,t+1,true,true,true);   WAIT_BAR(2); RESC(); ROT();
	ds_read_b64_tr_b16 v[186:187], v233 offset:24576
	ds_read_b64_tr_b16 v[188:189], v233 offset:25088
	s_waitcnt lgkmcnt(9)
	v_mfma_f32_32x32x16_bf16 v[82:97], v[60:63], v[158:161], v[2:17]
	v_add_f32_e32 v65, v114, v115
	v_add_f32_e32 v65, v116, v65
	v_add_f32_e32 v65, v117, v65
	v_add_f32_e32 v65, v118, v65
	v_add_f32_e32 v65, v119, v65
	v_cvt_pk_bf16_f32 v154, v114, v115
	v_cvt_pk_bf16_f32 v155, v116, v117
	ds_read_b64_tr_b16 v[60:61], v233 offset:28672
	ds_read_b64_tr_b16 v[62:63], v233 offset:29184
	s_waitcnt lgkmcnt(10)
	v_mfma_f32_32x32x16_bf16 v[66:81], v[162:165], v[158:161], v[2:17]
	v_add_f32_e32 v65, v120, v65
	v_add_f32_e32 v65, v121, v65
	v_add_f32_e32 v65, v122, v65
	v_add_f32_e32 v65, v123, v65
	v_cvt_pk_bf16_f32 v156, v118, v119
	v_cvt_pk_bf16_f32 v157, v120, v121
	ds_read_b64_tr_b16 v[114:115], v233 offset:25600
	ds_read_b64_tr_b16 v[116:117], v233 offset:26112
	s_waitcnt lgkmcnt(11)
	v_mfma_f32_32x32x16_bf16 v[82:97], v[166:169], v[150:153], v[82:97]
	v_add_f32_e32 v65, v124, v65
	v_add_f32_e32 v65, v125, v65
	v_add_f32_e32 v65, v126, v65
	v_add_f32_e32 v65, v127, v65
	v_cvt_pk_bf16_f32 v146, v122, v123
	v_cvt_pk_bf16_f32 v147, v124, v125
	ds_read_b64_tr_b16 v[118:119], v233 offset:29696
	ds_read_b64_tr_b16 v[120:121], v233 offset:30208
	s_waitcnt lgkmcnt(12)
	v_mfma_f32_32x32x16_bf16 v[66:81], v[170:173], v[150:153], v[66:81]
	v_add_f32_e32 v65, v128, v65
	v_add_f32_e32 v65, v129, v65
	v_add_f32_e32 v65, v98, v65
	v_add_f32_e32 v65, v99, v65
	v_cvt_pk_bf16_f32 v148, v126, v127
	v_cvt_pk_bf16_f32 v149, v128, v129
	ds_read_b64_tr_b16 v[122:123], v233 offset:26624
	ds_read_b64_tr_b16 v[124:125], v233 offset:27136
	s_waitcnt lgkmcnt(13)
	v_mfma_f32_32x32x16_bf16 v[82:97], v[174:177], v[142:145], v[82:97]
	v_add_f32_e32 v65, v100, v65
	v_add_f32_e32 v65, v101, v65
	v_add_f32_e32 v65, v102, v65
	v_add_f32_e32 v65, v103, v65
	v_cvt_pk_bf16_f32 v138, v98, v99
	v_cvt_pk_bf16_f32 v139, v100, v101
	ds_read_b64_tr_b16 v[98:99], v233 offset:30720
	ds_read_b64_tr_b16 v[100:101], v233 offset:31232
	s_waitcnt lgkmcnt(14)
	v_mfma_f32_32x32x16_bf16 v[66:81], v[178:181], v[142:145], v[66:81]
	v_add_f32_e32 v65, v104, v65
	v_add_f32_e32 v65, v105, v65
	v_add_f32_e32 v65, v106, v65
	v_add_f32_e32 v65, v107, v65
	v_cvt_pk_bf16_f32 v140, v102, v103
	v_cvt_pk_bf16_f32 v141, v104, v105
	ds_read_b64_tr_b16 v[102:103], v233 offset:27648
	ds_read_b64_tr_b16 v[104:105], v233 offset:28160
	s_waitcnt lgkmcnt(14)
	v_mfma_f32_32x32x16_bf16 v[82:97], v[182:185], v[134:137], v[82:97]
	v_add_f32_e32 v65, v108, v65
	v_add_f32_e32 v65, v109, v65
	v_add_f32_e32 v65, v110, v65
	v_add_f32_e32 v65, v111, v65
	v_cvt_pk_bf16_f32 v130, v106, v107
	v_cvt_pk_bf16_f32 v131, v108, v109
	ds_read_b64_tr_b16 v[106:107], v233 offset:31744
	ds_read_b64_tr_b16 v[108:109], v233 offset:32256
	v_mfma_f32_32x32x16_bf16 v[66:81], v[52:55], v[134:137], v[66:81]
	v_add_f32_e32 v52, v112, v65
	v_add_f32_e32 v52, v113, v52
	v_cvt_pk_bf16_f32 v132, v110, v111
	v_cvt_pk_bf16_f32 v133, v112, v113
	s_add_i32 m0, s18, 0x2000
	s_nop 0
	global_load_lds_dwordx4 v240, s[100:101]
	s_add_i32 m0, s19, 0x4000
	s_nop 0
	global_load_lds_dwordx4 v241, s[100:101]
	s_waitcnt lgkmcnt(14)
	v_mfma_f32_32x32x16_bf16 v[18:33], v[154:157], v[186:189], v[18:33]
	s_add_u32 s100, s100, 0x2000
	s_addc_u32 s101, s101, 0
	v_exp_f32_e32 v82, v82
	v_exp_f32_e32 v83, v83
	v_exp_f32_e32 v84, v84
	v_exp_f32_e32 v85, v85
	s_waitcnt lgkmcnt(12)
	v_mfma_f32_32x32x16_bf16 v[34:49], v[154:157], v[60:63], v[34:49]
	v_exp_f32_e32 v86, v86
	v_exp_f32_e32 v87, v87
	v_exp_f32_e32 v88, v88
	v_exp_f32_e32 v89, v89
	ds_read_b128 v[190:193], v230 offset:16384
	ds_read_b128 v[186:189], v230 offset:16896
	s_waitcnt lgkmcnt(12)
	v_mfma_f32_32x32x16_bf16 v[18:33], v[146:149], v[114:117], v[18:33]
	v_exp_f32_e32 v90, v90
	v_exp_f32_e32 v91, v91
	v_exp_f32_e32 v92, v92
	v_exp_f32_e32 v93, v93
	ds_read_b128 v[182:185], v230 offset:18432
	ds_read_b128 v[178:181], v230 offset:18944
	s_waitcnt lgkmcnt(12)
	v_mfma_f32_32x32x16_bf16 v[34:49], v[146:149], v[118:121], v[34:49]
	v_exp_f32_e32 v94, v94
	v_exp_f32_e32 v95, v95
	v_exp_f32_e32 v96, v96
	v_exp_f32_e32 v97, v97
	ds_read_b128 v[174:177], v230 offset:20480
	ds_read_b128 v[170:173], v230 offset:20992
	s_waitcnt lgkmcnt(12)
	v_mfma_f32_32x32x16_bf16 v[18:33], v[138:141], v[122:125], v[18:33]
	v_exp_f32_e32 v66, v66
	v_exp_f32_e32 v67, v67
	v_exp_f32_e32 v68, v68
	v_exp_f32_e32 v69, v69
	ds_read_b128 v[166:169], v230 offset:22528
	ds_read_b128 v[162:165], v230 offset:23040
	s_waitcnt lgkmcnt(12)
	v_mfma_f32_32x32x16_bf16 v[34:49], v[138:141], v[98:101], v[34:49]
	v_exp_f32_e32 v70, v70
	v_exp_f32_e32 v71, v71
	v_exp_f32_e32 v72, v72
	v_exp_f32_e32 v73, v73
	s_waitcnt lgkmcnt(10)
	v_mfma_f32_32x32x16_bf16 v[18:33], v[130:133], v[102:105], v[18:33]
	v_exp_f32_e32 v74, v74
	v_exp_f32_e32 v75, v75
	v_exp_f32_e32 v76, v76
	v_exp_f32_e32 v77, v77
	s_waitcnt lgkmcnt(8)
	v_mfma_f32_32x32x16_bf16 v[34:49], v[130:133], v[106:109], v[34:49]
	v_exp_f32_e32 v78, v78
	v_exp_f32_e32 v79, v79
	v_exp_f32_e32 v80, v80
	v_exp_f32_e32 v81, v81
	s_waitcnt vmcnt(2) lgkmcnt(0)
	s_barrier
; #define WAIT_BAR(N) asm volatile("s_waitcnt vmcnt(" #N ") lgkmcnt(0)\n\ts_barrier":::"memory")
;   #define RESC() do{ if(resc){ asm volatile("s_waitcnt lgkmcnt(0)":::"memory"); \
;       _Pragma("unroll") for(int d_=0;d_<2;++d_) _Pragma("unroll") for(int r=0;r<16;++r)o[d_][r]*=wsf[crow(r,hi)]; } }while(0)
;   #define ROT() do{sl_prev=sl_cur;sl_cur=sl_next;sl_next=(sl_next==(NSLOT-1)*SLOTB)?0:sl_next+SLOTB;}while(0)
; template<int THRL,bool FIXREF> __device__ __forceinline__ void attn_unit(const float*gq,const float*tab,const int tq0,const bf16*Qw0,const bf16*__restrict__ Kl,const bf16*__restrict__ Vl,const int NT,bf16*Ow0,char*shm){
;     ...
;   int t=1;
;     ...
;   for(;t+5<NT;t+=2){
;     STEP(pB0,pB1,pA0,pA1,t,true,true,true);     WAIT_BAR(2); RESC(); ROT();
;     STEP(pA0,pA1,pB0,pB1,t+1,true,true,true);   WAIT_BAR(2); RESC(); ROT();
	v_add_f32_e32 v50, v50, v51
	v_add_f32_e32 v50, v50, v52
	ds_read_b64_tr_b16 v[52:53], v233 offset:32768
	ds_read_b64_tr_b16 v[54:55], v233 offset:33280
	v_add_f32_e32 v60, v82, v83
	v_add_f32_e32 v60, v84, v60
	v_add_f32_e32 v60, v85, v60
	v_add_f32_e32 v60, v86, v60
	v_add_f32_e32 v64, v87, v60
	v_cvt_pk_bf16_f32 v154, v82, v83
	v_cvt_pk_bf16_f32 v155, v84, v85
	s_waitcnt lgkmcnt(9)
	v_mfma_f32_32x32x16_bf16 v[114:129], v[190:193], v[158:161], v[2:17]
	ds_read_b64_tr_b16 v[60:61], v233 offset:36864
	ds_read_b64_tr_b16 v[62:63], v233 offset:37376
	v_add_f32_e32 v64, v88, v64
	v_add_f32_e32 v64, v89, v64
	v_add_f32_e32 v64, v90, v64
	v_add_f32_e32 v64, v91, v64
	v_cvt_pk_bf16_f32 v156, v86, v87
	v_cvt_pk_bf16_f32 v157, v88, v89
	s_waitcnt lgkmcnt(10)
	v_mfma_f32_32x32x16_bf16 v[98:113], v[186:189], v[158:161], v[2:17]
	ds_read_b64_tr_b16 v[82:83], v233 offset:33792
	ds_read_b64_tr_b16 v[84:85], v233 offset:34304
	v_add_f32_e32 v64, v92, v64
	v_add_f32_e32 v64, v93, v64
	v_add_f32_e32 v64, v94, v64
	v_add_f32_e32 v64, v95, v64
	v_cvt_pk_bf16_f32 v146, v90, v91
	v_cvt_pk_bf16_f32 v147, v92, v93
	s_waitcnt lgkmcnt(11)
	v_mfma_f32_32x32x16_bf16 v[114:129], v[182:185], v[150:153], v[114:129]
	ds_read_b64_tr_b16 v[86:87], v233 offset:37888
	ds_read_b64_tr_b16 v[88:89], v233 offset:38400
	v_add_f32_e32 v64, v96, v64
	v_add_f32_e32 v64, v97, v64
	v_add_f32_e32 v64, v66, v64
	v_add_f32_e32 v64, v67, v64
	v_cvt_pk_bf16_f32 v148, v94, v95
	v_cvt_pk_bf16_f32 v149, v96, v97
	s_waitcnt lgkmcnt(12)
	v_mfma_f32_32x32x16_bf16 v[98:113], v[178:181], v[150:153], v[98:113]
	ds_read_b64_tr_b16 v[90:91], v233 offset:34816
	ds_read_b64_tr_b16 v[92:93], v233 offset:35328
	v_add_f32_e32 v64, v68, v64
	v_add_f32_e32 v64, v69, v64
	v_add_f32_e32 v64, v70, v64
	v_add_f32_e32 v94, v71, v64
	v_cvt_pk_bf16_f32 v138, v66, v67
	v_cvt_pk_bf16_f32 v139, v68, v69
	s_waitcnt lgkmcnt(13)
	v_mfma_f32_32x32x16_bf16 v[114:129], v[174:177], v[142:145], v[114:129]
	ds_read_b64_tr_b16 v[64:65], v233 offset:38912
	ds_read_b64_tr_b16 v[66:67], v233 offset:39424
	v_add_f32_e32 v68, v72, v94
	v_add_f32_e32 v68, v73, v68
	v_add_f32_e32 v68, v74, v68
	v_add_f32_e32 v94, v75, v68
	v_cvt_pk_bf16_f32 v140, v70, v71
	v_cvt_pk_bf16_f32 v141, v72, v73
	s_waitcnt lgkmcnt(14)
	v_mfma_f32_32x32x16_bf16 v[98:113], v[170:173], v[142:145], v[98:113]
	ds_read_b64_tr_b16 v[68:69], v233 offset:35840
	ds_read_b64_tr_b16 v[70:71], v233 offset:36352
	v_add_f32_e32 v72, v76, v94
	v_add_f32_e32 v72, v77, v72
	v_add_f32_e32 v72, v78, v72
	v_add_f32_e32 v94, v79, v72
	v_cvt_pk_bf16_f32 v130, v74, v75
	v_cvt_pk_bf16_f32 v131, v76, v77
	s_waitcnt lgkmcnt(14)
	v_mfma_f32_32x32x16_bf16 v[114:129], v[166:169], v[134:137], v[114:129]
	ds_read_b64_tr_b16 v[72:73], v233 offset:39936
	ds_read_b64_tr_b16 v[74:75], v233 offset:40448
	v_add_f32_e32 v51, v80, v94
	v_add_f32_e32 v51, v81, v51
	v_cvt_pk_bf16_f32 v132, v78, v79
	v_cvt_pk_bf16_f32 v133, v80, v81
	v_mfma_f32_32x32x16_bf16 v[98:113], v[162:165], v[134:137], v[98:113]
	s_add_i32 m0, s18, 0x4000
	s_nop 0
	global_load_lds_dwordx4 v240, s[100:101]
	s_mov_b32 m0, s19
	s_nop 0
	global_load_lds_dwordx4 v241, s[100:101]
	s_waitcnt lgkmcnt(14)
	v_mfma_f32_32x32x16_bf16 v[18:33], v[154:157], v[52:55], v[18:33]
	s_add_u32 s100, s100, 0x2000
	s_addc_u32 s101, s101, 0
	v_exp_f32_e32 v114, v114
	v_exp_f32_e32 v115, v115
	v_exp_f32_e32 v116, v116
	v_exp_f32_e32 v117, v117
	s_waitcnt lgkmcnt(12)
	v_mfma_f32_32x32x16_bf16 v[34:49], v[154:157], v[60:63], v[34:49]
	v_exp_f32_e32 v118, v118
	v_exp_f32_e32 v119, v119
	v_exp_f32_e32 v120, v120
	v_exp_f32_e32 v121, v121
	ds_read_b128 v[60:63], v230
	ds_read_b128 v[162:165], v230 offset:512
	s_waitcnt lgkmcnt(12)
	v_mfma_f32_32x32x16_bf16 v[18:33], v[146:149], v[82:85], v[18:33]
	v_exp_f32_e32 v122, v122
	v_exp_f32_e32 v123, v123
	v_exp_f32_e32 v124, v124
	v_exp_f32_e32 v125, v125
	ds_read_b128 v[166:169], v230 offset:2048
	ds_read_b128 v[170:173], v230 offset:2560
	s_waitcnt lgkmcnt(12)
	v_mfma_f32_32x32x16_bf16 v[34:49], v[146:149], v[86:89], v[34:49]
	v_exp_f32_e32 v126, v126
	v_exp_f32_e32 v127, v127
	v_exp_f32_e32 v128, v128
	v_exp_f32_e32 v129, v129
	ds_read_b128 v[174:177], v230 offset:4096
	ds_read_b128 v[178:181], v230 offset:4608
	s_waitcnt lgkmcnt(12)
	v_mfma_f32_32x32x16_bf16 v[18:33], v[138:141], v[90:93], v[18:33]
	v_exp_f32_e32 v98, v98
	v_exp_f32_e32 v99, v99
	v_exp_f32_e32 v100, v100
	v_exp_f32_e32 v101, v101
	ds_read_b128 v[182:185], v230 offset:6144
	ds_read_b128 v[52:55], v230 offset:6656
	s_waitcnt lgkmcnt(12)
	v_mfma_f32_32x32x16_bf16 v[34:49], v[138:141], v[64:67], v[34:49]
	v_exp_f32_e32 v102, v102
	v_exp_f32_e32 v103, v103
	v_exp_f32_e32 v104, v104
	v_exp_f32_e32 v105, v105
	s_waitcnt lgkmcnt(10)
	v_mfma_f32_32x32x16_bf16 v[18:33], v[130:133], v[68:71], v[18:33]
	v_exp_f32_e32 v106, v106
	v_exp_f32_e32 v107, v107
	v_exp_f32_e32 v108, v108
	v_exp_f32_e32 v109, v109
	s_waitcnt lgkmcnt(8)
	v_mfma_f32_32x32x16_bf16 v[34:49], v[130:133], v[72:75], v[34:49]
	v_exp_f32_e32 v110, v110
	v_exp_f32_e32 v111, v111
	v_exp_f32_e32 v112, v112
	v_exp_f32_e32 v113, v113
	s_waitcnt vmcnt(2) lgkmcnt(0)
	s_barrier
; #define WAIT_BAR(N) asm volatile("s_waitcnt vmcnt(" #N ") lgkmcnt(0)\n\ts_barrier":::"memory")
;   #define RESC() do{ if(resc){ asm volatile("s_waitcnt lgkmcnt(0)":::"memory"); \
;       _Pragma("unroll") for(int d_=0;d_<2;++d_) _Pragma("unroll") for(int r=0;r<16;++r)o[d_][r]*=wsf[crow(r,hi)]; } }while(0)
;   #define ROT() do{sl_prev=sl_cur;sl_cur=sl_next;sl_next=(sl_next==(NSLOT-1)*SLOTB)?0:sl_next+SLOTB;}while(0)
; template<int THRL,bool FIXREF> __device__ __forceinline__ void attn_unit(const float*gq,const float*tab,const int tq0,const bf16*Qw0,const bf16*__restrict__ Kl,const bf16*__restrict__ Vl,const int NT,bf16*Ow0,char*shm){
;     ...
;   int t=1;
;     ...
;   for(;t+5<NT;t+=2){
;     STEP(pB0,pB1,pA0,pA1,t,true,true,true);     WAIT_BAR(2); RESC(); ROT();
;     STEP(pA0,pA1,pB0,pB1,t+1,true,true,true);   WAIT_BAR(2); RESC(); ROT();
	ds_read_b64_tr_b16 v[186:187], v233 offset:40960
	ds_read_b64_tr_b16 v[188:189], v233 offset:41472
	s_waitcnt lgkmcnt(9)
	v_mfma_f32_32x32x16_bf16 v[82:97], v[60:63], v[158:161], v[2:17]
	v_add_f32_e32 v65, v114, v115
	v_add_f32_e32 v65, v116, v65
	v_add_f32_e32 v65, v117, v65
	v_add_f32_e32 v65, v118, v65
	v_add_f32_e32 v65, v119, v65
	v_cvt_pk_bf16_f32 v154, v114, v115
	v_cvt_pk_bf16_f32 v155, v116, v117
	ds_read_b64_tr_b16 v[60:61], v233 offset:45056
	ds_read_b64_tr_b16 v[62:63], v233 offset:45568
	s_waitcnt lgkmcnt(10)
	v_mfma_f32_32x32x16_bf16 v[66:81], v[162:165], v[158:161], v[2:17]
	v_add_f32_e32 v65, v120, v65
	v_add_f32_e32 v65, v121, v65
	v_add_f32_e32 v65, v122, v65
	v_add_f32_e32 v65, v123, v65
	v_cvt_pk_bf16_f32 v156, v118, v119
	v_cvt_pk_bf16_f32 v157, v120, v121
	ds_read_b64_tr_b16 v[114:115], v233 offset:41984
	ds_read_b64_tr_b16 v[116:117], v233 offset:42496
	s_waitcnt lgkmcnt(11)
	v_mfma_f32_32x32x16_bf16 v[82:97], v[166:169], v[150:153], v[82:97]
	v_add_f32_e32 v65, v124, v65
	v_add_f32_e32 v65, v125, v65
	v_add_f32_e32 v65, v126, v65
	v_add_f32_e32 v65, v127, v65
	v_cvt_pk_bf16_f32 v146, v122, v123
	v_cvt_pk_bf16_f32 v147, v124, v125
	ds_read_b64_tr_b16 v[118:119], v233 offset:46080
	ds_read_b64_tr_b16 v[120:121], v233 offset:46592
	s_waitcnt lgkmcnt(12)
	v_mfma_f32_32x32x16_bf16 v[66:81], v[170:173], v[150:153], v[66:81]
	v_add_f32_e32 v65, v128, v65
	v_add_f32_e32 v65, v129, v65
	v_add_f32_e32 v65, v98, v65
	v_add_f32_e32 v65, v99, v65
	v_cvt_pk_bf16_f32 v148, v126, v127
	v_cvt_pk_bf16_f32 v149, v128, v129
	ds_read_b64_tr_b16 v[122:123], v233 offset:43008
	ds_read_b64_tr_b16 v[124:125], v233 offset:43520
	s_waitcnt lgkmcnt(13)
	v_mfma_f32_32x32x16_bf16 v[82:97], v[174:177], v[142:145], v[82:97]
	v_add_f32_e32 v65, v100, v65
	v_add_f32_e32 v65, v101, v65
	v_add_f32_e32 v65, v102, v65
	v_add_f32_e32 v65, v103, v65
	v_cvt_pk_bf16_f32 v138, v98, v99
	v_cvt_pk_bf16_f32 v139, v100, v101
	ds_read_b64_tr_b16 v[98:99], v233 offset:47104
	ds_read_b64_tr_b16 v[100:101], v233 offset:47616
	s_waitcnt lgkmcnt(14)
	v_mfma_f32_32x32x16_bf16 v[66:81], v[178:181], v[142:145], v[66:81]
	v_add_f32_e32 v65, v104, v65
	v_add_f32_e32 v65, v105, v65
	v_add_f32_e32 v65, v106, v65
	v_add_f32_e32 v65, v107, v65
	v_cvt_pk_bf16_f32 v140, v102, v103
	v_cvt_pk_bf16_f32 v141, v104, v105
	ds_read_b64_tr_b16 v[102:103], v233 offset:44032
	ds_read_b64_tr_b16 v[104:105], v233 offset:44544
	s_waitcnt lgkmcnt(14)
	v_mfma_f32_32x32x16_bf16 v[82:97], v[182:185], v[134:137], v[82:97]
	v_add_f32_e32 v65, v108, v65
	v_add_f32_e32 v65, v109, v65
	v_add_f32_e32 v65, v110, v65
	v_add_f32_e32 v65, v111, v65
	v_cvt_pk_bf16_f32 v130, v106, v107
	v_cvt_pk_bf16_f32 v131, v108, v109
	ds_read_b64_tr_b16 v[106:107], v233 offset:48128
	ds_read_b64_tr_b16 v[108:109], v233 offset:48640
	v_mfma_f32_32x32x16_bf16 v[66:81], v[52:55], v[134:137], v[66:81]
	v_add_f32_e32 v52, v112, v65
	v_add_f32_e32 v52, v113, v52
	v_cvt_pk_bf16_f32 v132, v110, v111
	v_cvt_pk_bf16_f32 v133, v112, v113
	s_mov_b32 m0, s18
	s_nop 0
	global_load_lds_dwordx4 v240, s[100:101]
	s_add_i32 m0, s19, 0x2000
	s_nop 0
	global_load_lds_dwordx4 v241, s[100:101]
	s_waitcnt lgkmcnt(14)
	v_mfma_f32_32x32x16_bf16 v[18:33], v[154:157], v[186:189], v[18:33]
	s_add_u32 s100, s100, 0x2000
	s_addc_u32 s101, s101, 0
	v_exp_f32_e32 v82, v82
	v_exp_f32_e32 v83, v83
	v_exp_f32_e32 v84, v84
	v_exp_f32_e32 v85, v85
	s_waitcnt lgkmcnt(12)
	v_mfma_f32_32x32x16_bf16 v[34:49], v[154:157], v[60:63], v[34:49]
	v_exp_f32_e32 v86, v86
	v_exp_f32_e32 v87, v87
	v_exp_f32_e32 v88, v88
	v_exp_f32_e32 v89, v89
	ds_read_b128 v[190:193], v230 offset:8192
	ds_read_b128 v[186:189], v230 offset:8704
	s_waitcnt lgkmcnt(12)
	v_mfma_f32_32x32x16_bf16 v[18:33], v[146:149], v[114:117], v[18:33]
	v_exp_f32_e32 v90, v90
	v_exp_f32_e32 v91, v91
	v_exp_f32_e32 v92, v92
	v_exp_f32_e32 v93, v93
	ds_read_b128 v[182:185], v230 offset:10240
	ds_read_b128 v[178:181], v230 offset:10752
	s_waitcnt lgkmcnt(12)
	v_mfma_f32_32x32x16_bf16 v[34:49], v[146:149], v[118:121], v[34:49]
	v_exp_f32_e32 v94, v94
	v_exp_f32_e32 v95, v95
	v_exp_f32_e32 v96, v96
	v_exp_f32_e32 v97, v97
	ds_read_b128 v[174:177], v230 offset:12288
	ds_read_b128 v[170:173], v230 offset:12800
	s_waitcnt lgkmcnt(12)
	v_mfma_f32_32x32x16_bf16 v[18:33], v[138:141], v[122:125], v[18:33]
	v_exp_f32_e32 v66, v66
	v_exp_f32_e32 v67, v67
	v_exp_f32_e32 v68, v68
	v_exp_f32_e32 v69, v69
	ds_read_b128 v[166:169], v230 offset:14336
	ds_read_b128 v[162:165], v230 offset:14848
	s_waitcnt lgkmcnt(12)
	v_mfma_f32_32x32x16_bf16 v[34:49], v[138:141], v[98:101], v[34:49]
	v_exp_f32_e32 v70, v70
	v_exp_f32_e32 v71, v71
	v_exp_f32_e32 v72, v72
	v_exp_f32_e32 v73, v73
	s_waitcnt lgkmcnt(10)
	v_mfma_f32_32x32x16_bf16 v[18:33], v[130:133], v[102:105], v[18:33]
	v_exp_f32_e32 v74, v74
	v_exp_f32_e32 v75, v75
	v_exp_f32_e32 v76, v76
	v_exp_f32_e32 v77, v77
	s_waitcnt lgkmcnt(8)
	v_mfma_f32_32x32x16_bf16 v[34:49], v[130:133], v[106:109], v[34:49]
	v_exp_f32_e32 v78, v78
	v_exp_f32_e32 v79, v79
	v_exp_f32_e32 v80, v80
	v_exp_f32_e32 v81, v81
	s_waitcnt vmcnt(2) lgkmcnt(0)
	s_barrier
	v_add_f32_e32 v50, v50, v51
	v_add_f32_e32 v50, v50, v52
	s_add_i32 s10, s10, 6
	s_add_i32 s5, s10, 4
	s_cmp_lt_u32 s5, s55
	s_cbranch_scc1 .Lattn6
	s_cmp_lt_u32 s10, s55
	s_cbranch_scc1 .LBB0_278
	s_mov_b32 s4, 0
	s_add_i32 s5, s10, -2
	s_branch .Lattn6_exit
; #define WAIT_BAR(N) asm volatile("s_waitcnt vmcnt(" #N ") lgkmcnt(0)\n\ts_barrier":::"memory")
;   #define RESC() do{ if(resc){ asm volatile("s_waitcnt lgkmcnt(0)":::"memory"); \
;       _Pragma("unroll") for(int d_=0;d_<2;++d_) _Pragma("unroll") for(int r=0;r<16;++r)o[d_][r]*=wsf[crow(r,hi)]; } }while(0)
;   #define ROT() do{sl_prev=sl_cur;sl_cur=sl_next;sl_next=(sl_next==(NSLOT-1)*SLOTB)?0:sl_next+SLOTB;}while(0)
; template<int THRL,bool FIXREF> __device__ __forceinline__ void attn_unit(const float*gq,const float*tab,const int tq0,const bf16*Qw0,const bf16*__restrict__ Kl,const bf16*__restrict__ Vl,const int NT,bf16*Ow0,char*shm){
;     ...
;   int t=1;
;     ...
;   for(;t+5<NT;t+=2){
;     STEP(pB0,pB1,pA0,pA1,t,true,true,true);     WAIT_BAR(2); RESC(); ROT();
;     STEP(pA0,pA1,pB0,pB1,t+1,true,true,true);   WAIT_BAR(2); RESC(); ROT();
;   }
.LBB0_278:
	s_mov_b32 s4, s31
	s_mov_b32 s5, s10
	s_mov_b32 s6, s30
	v_add_u32_e32 v51, s7, v233
	ds_read_b64_tr_b16 v[52:53], v51 offset:24576
	ds_read_b64_tr_b16 v[54:55], v51 offset:25088
	v_add_f32_e32 v60, v82, v83
	v_add_f32_e32 v60, v84, v60
	v_add_f32_e32 v60, v85, v60
	v_add_f32_e32 v60, v86, v60
	v_add_f32_e32 v64, v87, v60
	v_cvt_pk_bf16_f32 v154, v82, v83
	v_cvt_pk_bf16_f32 v155, v84, v85
	s_waitcnt lgkmcnt(9)
	v_mfma_f32_32x32x16_bf16 v[114:129], v[190:193], v[158:161], v[2:17]
	ds_read_b64_tr_b16 v[60:61], v51 offset:28672
	ds_read_b64_tr_b16 v[62:63], v51 offset:29184
	v_add_f32_e32 v64, v88, v64
	v_add_f32_e32 v64, v89, v64
	v_add_f32_e32 v64, v90, v64
	v_add_f32_e32 v64, v91, v64
	v_cvt_pk_bf16_f32 v156, v86, v87
	v_cvt_pk_bf16_f32 v157, v88, v89
	s_waitcnt lgkmcnt(10)
	v_mfma_f32_32x32x16_bf16 v[98:113], v[186:189], v[158:161], v[2:17]
	ds_read_b64_tr_b16 v[82:83], v51 offset:25600
	ds_read_b64_tr_b16 v[84:85], v51 offset:26112
	v_add_f32_e32 v64, v92, v64
	v_add_f32_e32 v64, v93, v64
	v_add_f32_e32 v64, v94, v64
	v_add_f32_e32 v64, v95, v64
	v_cvt_pk_bf16_f32 v146, v90, v91
	v_cvt_pk_bf16_f32 v147, v92, v93
	s_waitcnt lgkmcnt(11)
	v_mfma_f32_32x32x16_bf16 v[114:129], v[182:185], v[150:153], v[114:129]
	ds_read_b64_tr_b16 v[86:87], v51 offset:29696
	ds_read_b64_tr_b16 v[88:89], v51 offset:30208
	v_add_f32_e32 v64, v96, v64
	v_add_f32_e32 v64, v97, v64
	v_add_f32_e32 v64, v66, v64
	v_add_f32_e32 v64, v67, v64
	v_cvt_pk_bf16_f32 v148, v94, v95
	v_cvt_pk_bf16_f32 v149, v96, v97
	s_waitcnt lgkmcnt(12)
	v_mfma_f32_32x32x16_bf16 v[98:113], v[178:181], v[150:153], v[98:113]
	ds_read_b64_tr_b16 v[90:91], v51 offset:26624
	ds_read_b64_tr_b16 v[92:93], v51 offset:27136
	v_add_f32_e32 v64, v68, v64
	v_add_f32_e32 v64, v69, v64
	v_add_f32_e32 v64, v70, v64
	v_add_f32_e32 v94, v71, v64
	v_cvt_pk_bf16_f32 v138, v66, v67
	v_cvt_pk_bf16_f32 v139, v68, v69
	s_waitcnt lgkmcnt(13)
	v_mfma_f32_32x32x16_bf16 v[114:129], v[174:177], v[142:145], v[114:129]
	ds_read_b64_tr_b16 v[64:65], v51 offset:30720
	ds_read_b64_tr_b16 v[66:67], v51 offset:31232
	v_add_f32_e32 v68, v72, v94
	v_add_f32_e32 v68, v73, v68
	v_add_f32_e32 v68, v74, v68
	v_add_f32_e32 v94, v75, v68
	v_cvt_pk_bf16_f32 v140, v70, v71
	v_cvt_pk_bf16_f32 v141, v72, v73
	s_waitcnt lgkmcnt(14)
	v_mfma_f32_32x32x16_bf16 v[98:113], v[170:173], v[142:145], v[98:113]
	ds_read_b64_tr_b16 v[68:69], v51 offset:27648
	ds_read_b64_tr_b16 v[70:71], v51 offset:28160
	v_add_f32_e32 v72, v76, v94
	v_add_f32_e32 v72, v77, v72
	v_add_f32_e32 v72, v78, v72
	v_add_f32_e32 v94, v79, v72
	v_cvt_pk_bf16_f32 v130, v74, v75
	v_cvt_pk_bf16_f32 v131, v76, v77
	s_waitcnt lgkmcnt(14)
	v_mfma_f32_32x32x16_bf16 v[114:129], v[166:169], v[134:137], v[114:129]
	ds_read_b64_tr_b16 v[72:73], v51 offset:31744
	ds_read_b64_tr_b16 v[74:75], v51 offset:32256
	v_add_f32_e32 v51, v80, v94
	v_add_f32_e32 v51, v81, v51
	v_add_f32_e32 v51, 0, v51
	v_cvt_pk_bf16_f32 v132, v78, v79
	v_cvt_pk_bf16_f32 v133, v80, v81
	v_mfma_f32_32x32x16_bf16 v[98:113], v[162:165], v[134:137], v[98:113]
	s_add_i32 m0, s30, s18
	s_nop 0
	global_load_lds_dwordx4 v240, s[100:101]
	s_add_i32 m0, s31, s19
	s_nop 0
	global_load_lds_dwordx4 v241, s[100:101]
	s_waitcnt lgkmcnt(14)
	v_mfma_f32_32x32x16_bf16 v[18:33], v[154:157], v[52:55], v[18:33]
	s_add_u32 s100, s100, 0x2000
	s_addc_u32 s101, s101, 0
	v_exp_f32_e32 v114, v114
	v_exp_f32_e32 v115, v115
	v_exp_f32_e32 v116, v116
	v_exp_f32_e32 v117, v117
	s_waitcnt lgkmcnt(12)
	v_mfma_f32_32x32x16_bf16 v[34:49], v[154:157], v[60:63], v[34:49]
	v_exp_f32_e32 v118, v118
	v_exp_f32_e32 v119, v119
	v_exp_f32_e32 v120, v120
	v_exp_f32_e32 v121, v121
	v_add_u32_e32 v52, s4, v230
	ds_read_b128 v[60:63], v52
	ds_read_b128 v[162:165], v52 offset:512
	s_waitcnt lgkmcnt(12)
	v_mfma_f32_32x32x16_bf16 v[18:33], v[146:149], v[82:85], v[18:33]
	v_exp_f32_e32 v122, v122
	v_exp_f32_e32 v123, v123
	v_exp_f32_e32 v124, v124
	v_exp_f32_e32 v125, v125
	ds_read_b128 v[166:169], v52 offset:2048
	ds_read_b128 v[170:173], v52 offset:2560
	s_waitcnt lgkmcnt(12)
	v_mfma_f32_32x32x16_bf16 v[34:49], v[146:149], v[86:89], v[34:49]
	v_exp_f32_e32 v126, v126
	v_exp_f32_e32 v127, v127
	v_exp_f32_e32 v128, v128
	v_exp_f32_e32 v129, v129
	ds_read_b128 v[174:177], v52 offset:4096
	ds_read_b128 v[178:181], v52 offset:4608
	s_waitcnt lgkmcnt(12)
	v_mfma_f32_32x32x16_bf16 v[18:33], v[138:141], v[90:93], v[18:33]
	v_exp_f32_e32 v98, v98
	v_exp_f32_e32 v99, v99
	v_exp_f32_e32 v100, v100
	v_exp_f32_e32 v101, v101
	ds_read_b128 v[182:185], v52 offset:6144
	ds_read_b128 v[52:55], v52 offset:6656
	s_waitcnt lgkmcnt(12)
	v_mfma_f32_32x32x16_bf16 v[34:49], v[138:141], v[64:67], v[34:49]
	v_exp_f32_e32 v102, v102
	v_exp_f32_e32 v103, v103
	v_exp_f32_e32 v104, v104
	v_exp_f32_e32 v105, v105
	s_waitcnt lgkmcnt(10)
	v_mfma_f32_32x32x16_bf16 v[18:33], v[130:133], v[68:71], v[18:33]
	v_exp_f32_e32 v106, v106
	v_exp_f32_e32 v107, v107
	v_exp_f32_e32 v108, v108
	v_exp_f32_e32 v109, v109
	s_waitcnt lgkmcnt(8)
	v_mfma_f32_32x32x16_bf16 v[34:49], v[130:133], v[72:75], v[34:49]
	v_exp_f32_e32 v110, v110
	v_exp_f32_e32 v111, v111
	v_exp_f32_e32 v112, v112
	v_exp_f32_e32 v113, v113
	s_waitcnt vmcnt(2) lgkmcnt(0)
	s_barrier
; #define WAIT_BAR(N) asm volatile("s_waitcnt vmcnt(" #N ") lgkmcnt(0)\n\ts_barrier":::"memory")
;   #define RESC() do{ if(resc){ asm volatile("s_waitcnt lgkmcnt(0)":::"memory"); \
;       _Pragma("unroll") for(int d_=0;d_<2;++d_) _Pragma("unroll") for(int r=0;r<16;++r)o[d_][r]*=wsf[crow(r,hi)]; } }while(0)
;   #define ROT() do{sl_prev=sl_cur;sl_cur=sl_next;sl_next=(sl_next==(NSLOT-1)*SLOTB)?0:sl_next+SLOTB;}while(0)
; template<int THRL,bool FIXREF> __device__ __forceinline__ void attn_unit(const float*gq,const float*tab,const int tq0,const bf16*Qw0,const bf16*__restrict__ Kl,const bf16*__restrict__ Vl,const int NT,bf16*Ow0,char*shm){
;     ...
;   int t=1;
;     ...
;   for(;t+5<NT;t+=2){
;     STEP(pB0,pB1,pA0,pA1,t,true,true,true);     WAIT_BAR(2); RESC(); ROT();
;     STEP(pA0,pA1,pB0,pB1,t+1,true,true,true);   WAIT_BAR(2); RESC(); ROT();
;   }
	s_add_i32 s7, s31, 0x2000
	s_cmpk_lg_i32 s31, 0x4000
	s_cselect_b32 s30, s7, 0
	v_add_u32_e32 v64, s6, v233
	ds_read_b64_tr_b16 v[186:187], v64 offset:24576
	ds_read_b64_tr_b16 v[188:189], v64 offset:25088
	s_waitcnt lgkmcnt(9)
	v_mfma_f32_32x32x16_bf16 v[82:97], v[60:63], v[158:161], v[2:17]
	v_add_f32_e32 v65, v114, v115
	v_add_f32_e32 v65, v116, v65
	v_add_f32_e32 v65, v117, v65
	v_add_f32_e32 v65, v118, v65
	v_add_f32_e32 v65, v119, v65
	v_cvt_pk_bf16_f32 v154, v114, v115
	v_cvt_pk_bf16_f32 v155, v116, v117
	ds_read_b64_tr_b16 v[60:61], v64 offset:28672
	ds_read_b64_tr_b16 v[62:63], v64 offset:29184
	s_waitcnt lgkmcnt(10)
	v_mfma_f32_32x32x16_bf16 v[66:81], v[162:165], v[158:161], v[2:17]
	v_add_f32_e32 v65, v120, v65
	v_add_f32_e32 v65, v121, v65
	v_add_f32_e32 v65, v122, v65
	v_add_f32_e32 v65, v123, v65
	v_cvt_pk_bf16_f32 v156, v118, v119
	v_cvt_pk_bf16_f32 v157, v120, v121
	ds_read_b64_tr_b16 v[114:115], v64 offset:25600
	ds_read_b64_tr_b16 v[116:117], v64 offset:26112
	s_waitcnt lgkmcnt(11)
	v_mfma_f32_32x32x16_bf16 v[82:97], v[166:169], v[150:153], v[82:97]
	v_add_f32_e32 v65, v124, v65
	v_add_f32_e32 v65, v125, v65
	v_add_f32_e32 v65, v126, v65
	v_add_f32_e32 v65, v127, v65
	v_cvt_pk_bf16_f32 v146, v122, v123
	v_cvt_pk_bf16_f32 v147, v124, v125
	ds_read_b64_tr_b16 v[118:119], v64 offset:29696
	ds_read_b64_tr_b16 v[120:121], v64 offset:30208
	s_waitcnt lgkmcnt(12)
	v_mfma_f32_32x32x16_bf16 v[66:81], v[170:173], v[150:153], v[66:81]
	v_add_f32_e32 v65, v128, v65
	v_add_f32_e32 v65, v129, v65
	v_add_f32_e32 v65, v98, v65
	v_add_f32_e32 v65, v99, v65
	v_cvt_pk_bf16_f32 v148, v126, v127
	v_cvt_pk_bf16_f32 v149, v128, v129
	ds_read_b64_tr_b16 v[122:123], v64 offset:26624
	ds_read_b64_tr_b16 v[124:125], v64 offset:27136
	s_waitcnt lgkmcnt(13)
	v_mfma_f32_32x32x16_bf16 v[82:97], v[174:177], v[142:145], v[82:97]
	v_add_f32_e32 v65, v100, v65
	v_add_f32_e32 v65, v101, v65
	v_add_f32_e32 v65, v102, v65
	v_add_f32_e32 v65, v103, v65
	v_cvt_pk_bf16_f32 v138, v98, v99
	v_cvt_pk_bf16_f32 v139, v100, v101
	ds_read_b64_tr_b16 v[98:99], v64 offset:30720
	ds_read_b64_tr_b16 v[100:101], v64 offset:31232
	s_waitcnt lgkmcnt(14)
	v_mfma_f32_32x32x16_bf16 v[66:81], v[178:181], v[142:145], v[66:81]
	v_add_f32_e32 v65, v104, v65
	v_add_f32_e32 v65, v105, v65
	v_add_f32_e32 v65, v106, v65
	v_add_f32_e32 v65, v107, v65
	v_cvt_pk_bf16_f32 v140, v102, v103
	v_cvt_pk_bf16_f32 v141, v104, v105
	ds_read_b64_tr_b16 v[102:103], v64 offset:27648
	ds_read_b64_tr_b16 v[104:105], v64 offset:28160
	s_waitcnt lgkmcnt(14)
	v_mfma_f32_32x32x16_bf16 v[82:97], v[182:185], v[134:137], v[82:97]
	v_add_f32_e32 v65, v108, v65
	v_add_f32_e32 v65, v109, v65
	v_add_f32_e32 v65, v110, v65
	v_add_f32_e32 v65, v111, v65
	v_cvt_pk_bf16_f32 v130, v106, v107
	v_cvt_pk_bf16_f32 v131, v108, v109
	ds_read_b64_tr_b16 v[106:107], v64 offset:31744
	ds_read_b64_tr_b16 v[108:109], v64 offset:32256
	v_mfma_f32_32x32x16_bf16 v[66:81], v[52:55], v[134:137], v[66:81]
	v_add_f32_e32 v52, v112, v65
	v_add_f32_e32 v52, v113, v52
	v_add_f32_e32 v52, 0, v52
	v_cvt_pk_bf16_f32 v132, v110, v111
	v_cvt_pk_bf16_f32 v133, v112, v113
	s_add_i32 m0, s31, s18
	s_nop 0
	global_load_lds_dwordx4 v240, s[100:101]
	s_add_i32 m0, s30, s19
	s_nop 0
	global_load_lds_dwordx4 v241, s[100:101]
	s_waitcnt lgkmcnt(14)
	v_mfma_f32_32x32x16_bf16 v[18:33], v[154:157], v[186:189], v[18:33]
	s_add_u32 s100, s100, 0x2000
	s_addc_u32 s101, s101, 0
	v_exp_f32_e32 v82, v82
	v_exp_f32_e32 v83, v83
	v_exp_f32_e32 v84, v84
	v_exp_f32_e32 v85, v85
	s_waitcnt lgkmcnt(12)
	v_mfma_f32_32x32x16_bf16 v[34:49], v[154:157], v[60:63], v[34:49]
	v_exp_f32_e32 v86, v86
	v_exp_f32_e32 v87, v87
	v_exp_f32_e32 v88, v88
	v_exp_f32_e32 v89, v89
	v_add_u32_e32 v53, s30, v230
	ds_read_b128 v[190:193], v53
	ds_read_b128 v[186:189], v53 offset:512
	s_waitcnt lgkmcnt(12)
	v_mfma_f32_32x32x16_bf16 v[18:33], v[146:149], v[114:117], v[18:33]
	v_exp_f32_e32 v90, v90
	v_exp_f32_e32 v91, v91
	v_exp_f32_e32 v92, v92
	v_exp_f32_e32 v93, v93
	ds_read_b128 v[182:185], v53 offset:2048
	ds_read_b128 v[178:181], v53 offset:2560
	s_waitcnt lgkmcnt(12)
	v_mfma_f32_32x32x16_bf16 v[34:49], v[146:149], v[118:121], v[34:49]
	v_exp_f32_e32 v94, v94
	v_exp_f32_e32 v95, v95
	v_exp_f32_e32 v96, v96
	v_exp_f32_e32 v97, v97
	ds_read_b128 v[174:177], v53 offset:4096
	ds_read_b128 v[170:173], v53 offset:4608
	s_waitcnt lgkmcnt(12)
	v_mfma_f32_32x32x16_bf16 v[18:33], v[138:141], v[122:125], v[18:33]
	v_exp_f32_e32 v66, v66
	v_exp_f32_e32 v67, v67
	v_exp_f32_e32 v68, v68
	v_exp_f32_e32 v69, v69
	ds_read_b128 v[166:169], v53 offset:6144
	ds_read_b128 v[162:165], v53 offset:6656
	s_waitcnt lgkmcnt(12)
	v_mfma_f32_32x32x16_bf16 v[34:49], v[138:141], v[98:101], v[34:49]
	v_exp_f32_e32 v70, v70
	v_exp_f32_e32 v71, v71
	v_exp_f32_e32 v72, v72
	v_exp_f32_e32 v73, v73
	s_waitcnt lgkmcnt(10)
	v_mfma_f32_32x32x16_bf16 v[18:33], v[130:133], v[102:105], v[18:33]
	v_exp_f32_e32 v74, v74
	v_exp_f32_e32 v75, v75
	v_exp_f32_e32 v76, v76
	v_exp_f32_e32 v77, v77
	s_waitcnt lgkmcnt(8)
	v_mfma_f32_32x32x16_bf16 v[34:49], v[130:133], v[106:109], v[34:49]
	v_exp_f32_e32 v78, v78
	v_exp_f32_e32 v79, v79
	v_exp_f32_e32 v80, v80
	v_exp_f32_e32 v81, v81
	s_add_i32 s6, s30, 0x2000
	s_waitcnt vmcnt(2) lgkmcnt(0)
	s_barrier
	s_cmpk_lg_i32 s30, 0x4000
	v_add_f32_e32 v50, v50, v51
	s_mov_b32 s7, s31
	s_cselect_b32 s31, s6, 0
	s_add_i32 s10, s5, 2
	s_cmp_ge_u32 s10, s55
	v_add_f32_e32 v50, v50, v52
	s_cbranch_scc0 .LBB0_278
.Lattn6_exit:
	s_add_i32 s10, s5, -3
	s_add_i32 s5, s10, 1
	s_cmp_ge_u32 s5, s55
	s_cbranch_scc0 .LBB0_288

; __global__ void __launch_bounds__(512, 2) fwd_megakernel(Args args) {
	.amdhsa_kernel _Z14fwd_megakernel4Args
		.amdhsa_group_segment_fixed_size 0
		.amdhsa_private_segment_fixed_size 0
		.amdhsa_kernarg_size 408
		.amdhsa_user_sgpr_count 2
		.amdhsa_user_sgpr_dispatch_ptr 0
		.amdhsa_user_sgpr_queue_ptr 0
		.amdhsa_user_sgpr_kernarg_segment_ptr 1
		.amdhsa_user_sgpr_dispatch_id 0
		.amdhsa_user_sgpr_kernarg_preload_length 0
		.amdhsa_user_sgpr_kernarg_preload_offset 0
		.amdhsa_user_sgpr_private_segment_size 0
		.amdhsa_uses_dynamic_stack 0
		.amdhsa_enable_private_segment 0
		.amdhsa_system_sgpr_workgroup_id_x 1
		.amdhsa_system_sgpr_workgroup_id_y 0
		.amdhsa_system_sgpr_workgroup_id_z 0
		.amdhsa_system_sgpr_workgroup_info 0
		.amdhsa_system_vgpr_workitem_id 2
		.amdhsa_next_free_vgpr 248
		.amdhsa_next_free_sgpr 102
		.amdhsa_accum_offset 248
		.amdhsa_reserve_vcc 1
		.amdhsa_float_round_mode_32 0
		.amdhsa_float_round_mode_16_64 0
		.amdhsa_float_denorm_mode_32 3
		.amdhsa_float_denorm_mode_16_64 3
		.amdhsa_dx10_clamp 1
		.amdhsa_ieee_mode 1
		.amdhsa_fp16_overflow 0
		.amdhsa_tg_split 0
		.amdhsa_exception_fp_ieee_invalid_op 0
		.amdhsa_exception_fp_denorm_src 0
		.amdhsa_exception_fp_ieee_div_zero 0
		.amdhsa_exception_fp_ieee_overflow 0
		.amdhsa_exception_fp_ieee_underflow 0
		.amdhsa_exception_fp_ieee_inexact 0
		.amdhsa_exception_int_div_zero 0
	.end_amdhsa_kernel

; __global__ void __launch_bounds__(512, 2) fwd_megakernel(Args args) {
amdhsa.kernels:
  - .agpr_count:     0
    .args:
      - .offset:         0
        .size:           152
        .value_kind:     by_value
      - .offset:         152
        .size:           4
        .value_kind:     hidden_block_count_x
      - .offset:         156
        .size:           4
        .value_kind:     hidden_block_count_y
      - .offset:         160
        .size:           4
        .value_kind:     hidden_block_count_z
      - .offset:         164
        .size:           2
        .value_kind:     hidden_group_size_x
      - .offset:         166
        .size:           2
        .value_kind:     hidden_group_size_y
      - .offset:         168
        .size:           2
        .value_kind:     hidden_group_size_z
      - .offset:         170
        .size:           2
        .value_kind:     hidden_remainder_x
      - .offset:         172
        .size:           2
        .value_kind:     hidden_remainder_y
      - .offset:         174
        .size:           2
        .value_kind:     hidden_remainder_z
      - .offset:         192
        .size:           8
        .value_kind:     hidden_global_offset_x
      - .offset:         200
        .size:           8
        .value_kind:     hidden_global_offset_y
      - .offset:         208
        .size:           8
        .value_kind:     hidden_global_offset_z
      - .offset:         216
        .size:           2
        .value_kind:     hidden_grid_dims
      - .offset:         240
        .size:           8
        .value_kind:     hidden_multigrid_sync_arg
      - .offset:         272
        .size:           4
        .value_kind:     hidden_dynamic_lds_size
    .group_segment_fixed_size: 0
    .kernarg_segment_align: 8
    .kernarg_segment_size: 408
    .language:       OpenCL C
    .language_version:
      - 2
      - 0
    .max_flat_workgroup_size: 512
    .name:           _Z14fwd_megakernel4Args
    .private_segment_fixed_size: 0
    .sgpr_count:     108
    .sgpr_spill_count: 113
    .symbol:         _Z14fwd_megakernel4Args.kd
    .uniform_work_group_size: 1
    .uses_dynamic_stack: false
    .vgpr_count:     248
    .vgpr_spill_count: 0
    .wavefront_size: 64
